# phase-3 gate epilogues: 16 serialised sb loads (final) and 16 serialised (sa,sb) pairs (mid hook) issued in batches with one wait each; stacked on prepare + bgate hoist
# speedup vs baseline: 1.0040x; 1.0040x over previous
; __device__ __forceinline__ float bf_lo(unsigned w) { return __uint_as_float(w << 16); }
; __device__ __forceinline__ float bf_hi(unsigned w) { return __uint_as_float(w & 0xffff0000u); }
;     __device__ __forceinline__ void mid(f32x4 (&acc)[2][2][4][2], const pg8::Unit& u, int wr, int wc, int fr, int fq) const {
;         int row0 = u.pm * 256 + wr * 64 + fr, c0 = u.pn * 256 + wc * 64 + 16 * fq;
;         asm volatile("" : "+v"(row0), "+v"(c0));
; #pragma unroll
;         for (int ai = 0; ai < 2; ++ai)
; #pragma unroll
;             for (int m = 0; m < 4; ++m)
; #pragma unroll
;                 for (int bj = 0; bj < 2; ++bj) {
;                     const size_t off = (size_t)(row0 + ai * 128 + m * 16) * D + c0 + bj * 8;
;                     const u32x4 a = *(const u32x4*)(sa + off), b = *(const u32x4*)(sb + off);
;                     f32x4 r0, r1;
;                     r0[0] = bf_lo(a.x) * __builtin_amdgcn_rcpf(bf_lo(b.x)); r0[1] = bf_hi(a.x) * __builtin_amdgcn_rcpf(bf_hi(b.x)); r0[2] = bf_lo(a.y) * __builtin_amdgcn_rcpf(bf_lo(b.y)); r0[3] = bf_hi(a.y) * __builtin_amdgcn_rcpf(bf_hi(b.y));
;                     r1[0] = bf_lo(a.z) * __builtin_amdgcn_rcpf(bf_lo(b.z)); r1[1] = bf_hi(a.z) * __builtin_amdgcn_rcpf(bf_hi(b.z)); r1[2] = bf_lo(a.w) * __builtin_amdgcn_rcpf(bf_lo(b.w)); r1[3] = bf_hi(a.w) * __builtin_amdgcn_rcpf(bf_hi(b.w));
;                     acc[ai][bj][m][0] *= r0; acc[ai][bj][m][1] *= r1;
;                     if ((m & 1) && bj == 1) asm volatile("" ::: "memory");
;                 }
.LBB0_465:
	s_cmp_lg_u32 s2, 1
	s_cbranch_scc1 .LBB0_454
	v_mov_b32_e32 v2, v148
	v_mov_b32_e32 v132, v150
	s_mov_b64 s[36:37], 0x90000
	v_ashrrev_i32_e32 v133, 31, v132
	v_ashrrev_i32_e32 v3, 31, v2
	v_lshlrev_b64 v[132:133], 11, v[132:133]
	v_lshl_add_u64 v[2:3], v[132:133], 0, v[2:3]
	v_lshlrev_b64 v[2:3], 1, v[2:3]
	v_lshl_add_u64 v[156:157], s[82:83], 0, v[2:3]
	v_lshl_add_u64 v[158:159], s[84:85], 0, v[2:3]
	v_lshlrev_b32_e32 v164, 11, v150
	v_add_lshl_u32 v164, v164, v148, 1
	v_mov_b32_e32 v165, v164
	global_load_dwordx4 v[172:175], v165, s[82:83]
	global_load_dwordx4 v[176:179], v165, s[84:85]
	global_load_dwordx4 v[180:183], v165, s[82:83] offset:16
	global_load_dwordx4 v[184:187], v165, s[84:85] offset:16
	v_add_u32_e32 v165, 0x10000, v164
	global_load_dwordx4 v[188:191], v165, s[82:83]
	global_load_dwordx4 v[192:195], v165, s[84:85]
	global_load_dwordx4 v[196:199], v165, s[82:83] offset:16
	global_load_dwordx4 v[212:215], v165, s[84:85] offset:16
	v_add_u32_e32 v165, 0x20000, v164
	global_load_dwordx4 v[216:219], v165, s[82:83]
	global_load_dwordx4 v[220:223], v165, s[84:85]
	global_load_dwordx4 v[224:227], v165, s[82:83] offset:16
	global_load_dwordx4 v[228:231], v165, s[84:85] offset:16
	v_add_u32_e32 v165, 0x30000, v164
	global_load_dwordx4 v[232:235], v165, s[82:83]
	global_load_dwordx4 v[236:239], v165, s[84:85]
	global_load_dwordx4 v[240:243], v165, s[82:83] offset:16
	global_load_dwordx4 v[244:247], v165, s[84:85] offset:16
	s_waitcnt vmcnt(0) lgkmcnt(0)
	v_mov_b32_e32 v132, v172
	v_mov_b32_e32 v133, v173
	v_mov_b32_e32 v134, v174
	v_mov_b32_e32 v135, v175
	v_mov_b32_e32 v136, v176
	v_mov_b32_e32 v137, v177
	v_mov_b32_e32 v138, v178
	v_mov_b32_e32 v139, v179
	v_lshlrev_b32_e32 v162, 16, v132
	v_lshlrev_b32_e32 v0, 16, v136
	v_rcp_f32_e32 v160, v0
	v_and_b32_e32 v0, 0xffff0000, v136
	v_rcp_f32_e32 v161, v0
	v_lshlrev_b32_e32 v0, 16, v137
	v_rcp_f32_e32 v136, v0
	v_and_b32_e32 v0, 0xffff0000, v137
	v_rcp_f32_e32 v137, v0
	v_and_b32_e32 v163, 0xffff0000, v132
	v_lshlrev_b32_e32 v132, 16, v133
	v_and_b32_e32 v133, 0xffff0000, v133
	v_lshlrev_b32_e32 v0, 16, v138
	v_pk_mul_f32 v[132:133], v[136:137], v[132:133]
	v_rcp_f32_e32 v136, v0
	v_and_b32_e32 v0, 0xffff0000, v138
	v_rcp_f32_e32 v137, v0
	v_lshlrev_b32_e32 v0, 16, v139
	v_rcp_f32_e32 v138, v0
	v_and_b32_e32 v0, 0xffff0000, v139
	v_rcp_f32_e32 v139, v0
	v_pk_mul_f32 v[160:161], v[160:161], v[162:163]
	v_lshlrev_b32_e32 v162, 16, v134
	v_and_b32_e32 v163, 0xffff0000, v134
	v_lshlrev_b32_e32 v134, 16, v135
	v_and_b32_e32 v135, 0xffff0000, v135
	v_pk_mul_f32 v[136:137], v[136:137], v[162:163]
	v_pk_mul_f32 v[134:135], v[138:139], v[134:135]
	v_pk_mul_f32 v[130:131], v[130:131], v[132:133]
	v_pk_mul_f32 v[126:127], v[126:127], v[134:135]
	v_pk_mul_f32 v[124:125], v[124:125], v[136:137]
	v_pk_mul_f32 v[128:129], v[128:129], v[160:161]
	v_mov_b32_e32 v132, v180
	v_mov_b32_e32 v133, v181
	v_mov_b32_e32 v134, v182
	v_mov_b32_e32 v135, v183
	v_mov_b32_e32 v136, v184
	v_mov_b32_e32 v137, v185
	v_mov_b32_e32 v138, v186
	v_mov_b32_e32 v139, v187
	v_lshlrev_b32_e32 v158, 16, v132
	v_lshlrev_b32_e32 v0, 16, v136
	v_rcp_f32_e32 v156, v0
	v_and_b32_e32 v0, 0xffff0000, v136
	v_rcp_f32_e32 v157, v0
	v_lshlrev_b32_e32 v0, 16, v137
	v_rcp_f32_e32 v136, v0
	v_and_b32_e32 v0, 0xffff0000, v137
	v_rcp_f32_e32 v137, v0
	v_and_b32_e32 v159, 0xffff0000, v132
	v_lshlrev_b32_e32 v132, 16, v133
	v_and_b32_e32 v133, 0xffff0000, v133
	v_lshlrev_b32_e32 v0, 16, v138
	v_pk_mul_f32 v[132:133], v[136:137], v[132:133]
	v_rcp_f32_e32 v136, v0
	v_and_b32_e32 v0, 0xffff0000, v138
	v_rcp_f32_e32 v137, v0
	v_lshlrev_b32_e32 v0, 16, v139
	v_rcp_f32_e32 v138, v0
	v_and_b32_e32 v0, 0xffff0000, v139
	v_rcp_f32_e32 v139, v0
	v_pk_mul_f32 v[156:157], v[156:157], v[158:159]
	v_lshlrev_b32_e32 v158, 16, v134
	v_and_b32_e32 v159, 0xffff0000, v134
	v_pk_mul_f32 v[136:137], v[136:137], v[158:159]
	v_lshlrev_b32_e32 v134, 16, v135
	v_and_b32_e32 v135, 0xffff0000, v135
	v_pk_mul_f32 v[116:117], v[116:117], v[136:137]
	v_lshl_add_u64 v[136:137], v[2:3], 0, s[58:59]
	v_pk_mul_f32 v[134:135], v[138:139], v[134:135]
	v_pk_mul_f32 v[120:121], v[120:121], v[156:157]
	v_lshl_add_u64 v[156:157], s[82:83], 0, v[136:137]
	v_lshl_add_u64 v[158:159], s[84:85], 0, v[136:137]
	v_pk_mul_f32 v[122:123], v[122:123], v[132:133]
	v_pk_mul_f32 v[118:119], v[118:119], v[134:135]
	v_mov_b32_e32 v132, v188
	v_mov_b32_e32 v133, v189
	v_mov_b32_e32 v134, v190
	v_mov_b32_e32 v135, v191
	v_mov_b32_e32 v136, v192
	v_mov_b32_e32 v137, v193
	v_mov_b32_e32 v138, v194
	v_mov_b32_e32 v139, v195
	v_lshlrev_b32_e32 v162, 16, v132
	v_lshlrev_b32_e32 v0, 16, v136
	v_rcp_f32_e32 v160, v0
	v_and_b32_e32 v0, 0xffff0000, v136
	v_rcp_f32_e32 v161, v0
	v_lshlrev_b32_e32 v0, 16, v137
	v_rcp_f32_e32 v136, v0
	v_and_b32_e32 v0, 0xffff0000, v137
	v_rcp_f32_e32 v137, v0
	v_and_b32_e32 v163, 0xffff0000, v132
	v_lshlrev_b32_e32 v132, 16, v133
	v_and_b32_e32 v133, 0xffff0000, v133
	v_lshlrev_b32_e32 v0, 16, v138
	v_pk_mul_f32 v[132:133], v[136:137], v[132:133]
	v_rcp_f32_e32 v136, v0
	v_and_b32_e32 v0, 0xffff0000, v138
	v_rcp_f32_e32 v137, v0
	v_lshlrev_b32_e32 v0, 16, v139
	v_rcp_f32_e32 v138, v0
	v_and_b32_e32 v0, 0xffff0000, v139
	v_rcp_f32_e32 v139, v0
	v_pk_mul_f32 v[160:161], v[160:161], v[162:163]
	v_lshlrev_b32_e32 v162, 16, v134
	v_and_b32_e32 v163, 0xffff0000, v134
	v_lshlrev_b32_e32 v134, 16, v135
	v_and_b32_e32 v135, 0xffff0000, v135
	v_pk_mul_f32 v[136:137], v[136:137], v[162:163]
	v_pk_mul_f32 v[134:135], v[138:139], v[134:135]
	v_pk_mul_f32 v[114:115], v[114:115], v[132:133]
	v_pk_mul_f32 v[110:111], v[110:111], v[134:135]
	v_pk_mul_f32 v[108:109], v[108:109], v[136:137]
; __device__ __forceinline__ float bf_lo(unsigned w) { return __uint_as_float(w << 16); }
; __device__ __forceinline__ float bf_hi(unsigned w) { return __uint_as_float(w & 0xffff0000u); }
;     __device__ __forceinline__ void mid(f32x4 (&acc)[2][2][4][2], const pg8::Unit& u, int wr, int wc, int fr, int fq) const {
;     ...
;         for (int ai = 0; ai < 2; ++ai)
; #pragma unroll
;             for (int m = 0; m < 4; ++m)
; #pragma unroll
;                 for (int bj = 0; bj < 2; ++bj) {
;                     const size_t off = (size_t)(row0 + ai * 128 + m * 16) * D + c0 + bj * 8;
;                     const u32x4 a = *(const u32x4*)(sa + off), b = *(const u32x4*)(sb + off);
;                     f32x4 r0, r1;
;                     r0[0] = bf_lo(a.x) * __builtin_amdgcn_rcpf(bf_lo(b.x)); r0[1] = bf_hi(a.x) * __builtin_amdgcn_rcpf(bf_hi(b.x)); r0[2] = bf_lo(a.y) * __builtin_amdgcn_rcpf(bf_lo(b.y)); r0[3] = bf_hi(a.y) * __builtin_amdgcn_rcpf(bf_hi(b.y));
;                     r1[0] = bf_lo(a.z) * __builtin_amdgcn_rcpf(bf_lo(b.z)); r1[1] = bf_hi(a.z) * __builtin_amdgcn_rcpf(bf_hi(b.z)); r1[2] = bf_lo(a.w) * __builtin_amdgcn_rcpf(bf_lo(b.w)); r1[3] = bf_hi(a.w) * __builtin_amdgcn_rcpf(bf_hi(b.w));
;                     acc[ai][bj][m][0] *= r0; acc[ai][bj][m][1] *= r1;
;                     if ((m & 1) && bj == 1) asm volatile("" ::: "memory");
;                 }
	v_pk_mul_f32 v[112:113], v[112:113], v[160:161]
	v_mov_b32_e32 v132, v196
	v_mov_b32_e32 v133, v197
	v_mov_b32_e32 v134, v198
	v_mov_b32_e32 v135, v199
	v_mov_b32_e32 v136, v212
	v_mov_b32_e32 v137, v213
	v_mov_b32_e32 v138, v214
	v_mov_b32_e32 v139, v215
	v_lshlrev_b32_e32 v158, 16, v132
	v_lshlrev_b32_e32 v0, 16, v136
	v_rcp_f32_e32 v156, v0
	v_and_b32_e32 v0, 0xffff0000, v136
	v_rcp_f32_e32 v157, v0
	v_lshlrev_b32_e32 v0, 16, v137
	v_rcp_f32_e32 v136, v0
	v_and_b32_e32 v0, 0xffff0000, v137
	v_rcp_f32_e32 v137, v0
	v_and_b32_e32 v159, 0xffff0000, v132
	v_lshlrev_b32_e32 v132, 16, v133
	v_and_b32_e32 v133, 0xffff0000, v133
	v_lshlrev_b32_e32 v0, 16, v138
	v_pk_mul_f32 v[132:133], v[136:137], v[132:133]
	v_rcp_f32_e32 v136, v0
	v_and_b32_e32 v0, 0xffff0000, v138
	v_rcp_f32_e32 v137, v0
	v_lshlrev_b32_e32 v0, 16, v139
	v_rcp_f32_e32 v138, v0
	v_and_b32_e32 v0, 0xffff0000, v139
	v_rcp_f32_e32 v139, v0
	v_pk_mul_f32 v[156:157], v[156:157], v[158:159]
	v_lshlrev_b32_e32 v158, 16, v134
	v_and_b32_e32 v159, 0xffff0000, v134
	v_pk_mul_f32 v[136:137], v[136:137], v[158:159]
	v_lshlrev_b32_e32 v134, 16, v135
	v_and_b32_e32 v135, 0xffff0000, v135
	v_pk_mul_f32 v[100:101], v[100:101], v[136:137]
	v_lshl_add_u64 v[136:137], v[2:3], 0, s[54:55]
	v_pk_mul_f32 v[134:135], v[138:139], v[134:135]
	v_lshl_add_u64 v[138:139], s[82:83], 0, v[136:137]
	v_lshl_add_u64 v[136:137], s[84:85], 0, v[136:137]
	v_pk_mul_f32 v[106:107], v[106:107], v[132:133]
	v_pk_mul_f32 v[104:105], v[104:105], v[156:157]
	v_pk_mul_f32 v[102:103], v[102:103], v[134:135]
	v_mov_b32_e32 v132, v216
	v_mov_b32_e32 v133, v217
	v_mov_b32_e32 v134, v218
	v_mov_b32_e32 v135, v219
	v_mov_b32_e32 v156, v220
	v_mov_b32_e32 v157, v221
	v_mov_b32_e32 v158, v222
	v_mov_b32_e32 v159, v223
	v_lshlrev_b32_e32 v162, 16, v132
	v_lshlrev_b32_e32 v0, 16, v156
	v_rcp_f32_e32 v160, v0
	v_and_b32_e32 v0, 0xffff0000, v156
	v_rcp_f32_e32 v161, v0
	v_lshlrev_b32_e32 v0, 16, v157
	v_rcp_f32_e32 v156, v0
	v_and_b32_e32 v0, 0xffff0000, v157
	v_rcp_f32_e32 v157, v0
	v_and_b32_e32 v163, 0xffff0000, v132
	v_lshlrev_b32_e32 v132, 16, v133
	v_and_b32_e32 v133, 0xffff0000, v133
	v_lshlrev_b32_e32 v0, 16, v158
	v_pk_mul_f32 v[132:133], v[156:157], v[132:133]
	v_rcp_f32_e32 v156, v0
	v_and_b32_e32 v0, 0xffff0000, v158
	v_rcp_f32_e32 v157, v0
	v_lshlrev_b32_e32 v0, 16, v159
	v_rcp_f32_e32 v158, v0
	v_and_b32_e32 v0, 0xffff0000, v159
	v_rcp_f32_e32 v159, v0
	v_pk_mul_f32 v[160:161], v[160:161], v[162:163]
	v_lshlrev_b32_e32 v162, 16, v134
	v_and_b32_e32 v163, 0xffff0000, v134
	v_lshlrev_b32_e32 v134, 16, v135
	v_and_b32_e32 v135, 0xffff0000, v135
	v_pk_mul_f32 v[134:135], v[158:159], v[134:135]
	v_pk_mul_f32 v[98:99], v[98:99], v[132:133]
	v_pk_mul_f32 v[94:95], v[94:95], v[134:135]
	s_nop 0
	v_pk_mul_f32 v[156:157], v[156:157], v[162:163]
	v_pk_mul_f32 v[96:97], v[96:97], v[160:161]
	v_pk_mul_f32 v[92:93], v[92:93], v[156:157]
	v_mov_b32_e32 v132, v224
	v_mov_b32_e32 v133, v225
	v_mov_b32_e32 v134, v226
	v_mov_b32_e32 v135, v227
	v_mov_b32_e32 v136, v228
	v_mov_b32_e32 v137, v229
	v_mov_b32_e32 v138, v230
	v_mov_b32_e32 v139, v231
	v_lshlrev_b32_e32 v158, 16, v132
	v_lshlrev_b32_e32 v0, 16, v136
	v_rcp_f32_e32 v156, v0
	v_and_b32_e32 v0, 0xffff0000, v136
	v_rcp_f32_e32 v157, v0
	v_lshlrev_b32_e32 v0, 16, v137
	v_rcp_f32_e32 v136, v0
	v_and_b32_e32 v0, 0xffff0000, v137
	v_rcp_f32_e32 v137, v0
	v_and_b32_e32 v159, 0xffff0000, v132
	v_lshlrev_b32_e32 v132, 16, v133
	v_and_b32_e32 v133, 0xffff0000, v133
	v_lshlrev_b32_e32 v0, 16, v138
	v_pk_mul_f32 v[132:133], v[136:137], v[132:133]
	v_rcp_f32_e32 v136, v0
	v_and_b32_e32 v0, 0xffff0000, v138
	v_rcp_f32_e32 v137, v0
	v_lshlrev_b32_e32 v0, 16, v139
	v_rcp_f32_e32 v138, v0
	v_and_b32_e32 v0, 0xffff0000, v139
	v_rcp_f32_e32 v139, v0
	v_pk_mul_f32 v[156:157], v[156:157], v[158:159]
	v_lshlrev_b32_e32 v158, 16, v134
	v_and_b32_e32 v159, 0xffff0000, v134
	v_pk_mul_f32 v[136:137], v[136:137], v[158:159]
	v_lshlrev_b32_e32 v134, 16, v135
	v_and_b32_e32 v135, 0xffff0000, v135
	v_pk_mul_f32 v[84:85], v[84:85], v[136:137]
	v_lshl_add_u64 v[136:137], v[2:3], 0, s[60:61]
	v_pk_mul_f32 v[134:135], v[138:139], v[134:135]
	v_lshl_add_u64 v[138:139], s[82:83], 0, v[136:137]
	v_lshl_add_u64 v[136:137], s[84:85], 0, v[136:137]
	v_pk_mul_f32 v[90:91], v[90:91], v[132:133]
	v_pk_mul_f32 v[88:89], v[88:89], v[156:157]
	v_pk_mul_f32 v[86:87], v[86:87], v[134:135]
	v_mov_b32_e32 v132, v232
	v_mov_b32_e32 v133, v233
	v_mov_b32_e32 v134, v234
	v_mov_b32_e32 v135, v235
	v_mov_b32_e32 v156, v236
	v_mov_b32_e32 v157, v237
	v_mov_b32_e32 v158, v238
	v_mov_b32_e32 v159, v239
	v_lshlrev_b32_e32 v162, 16, v132
	v_lshlrev_b32_e32 v0, 16, v156
	v_rcp_f32_e32 v160, v0
	v_and_b32_e32 v0, 0xffff0000, v156
	v_rcp_f32_e32 v161, v0
	v_lshlrev_b32_e32 v0, 16, v157
	v_rcp_f32_e32 v156, v0
	v_and_b32_e32 v0, 0xffff0000, v157
	v_rcp_f32_e32 v157, v0
	v_and_b32_e32 v163, 0xffff0000, v132
	v_lshlrev_b32_e32 v132, 16, v133
	v_and_b32_e32 v133, 0xffff0000, v133
	v_lshlrev_b32_e32 v0, 16, v158
	v_pk_mul_f32 v[132:133], v[156:157], v[132:133]
	v_rcp_f32_e32 v156, v0
	v_and_b32_e32 v0, 0xffff0000, v158
	v_rcp_f32_e32 v157, v0
	v_lshlrev_b32_e32 v0, 16, v159
	v_rcp_f32_e32 v158, v0
	v_and_b32_e32 v0, 0xffff0000, v159
	v_rcp_f32_e32 v159, v0
	v_pk_mul_f32 v[160:161], v[160:161], v[162:163]
	v_lshlrev_b32_e32 v162, 16, v134
	v_and_b32_e32 v163, 0xffff0000, v134
	v_lshlrev_b32_e32 v134, 16, v135
	v_and_b32_e32 v135, 0xffff0000, v135
	v_pk_mul_f32 v[134:135], v[158:159], v[134:135]
	v_pk_mul_f32 v[82:83], v[82:83], v[132:133]
	v_pk_mul_f32 v[78:79], v[78:79], v[134:135]
	s_nop 0
	v_pk_mul_f32 v[156:157], v[156:157], v[162:163]
; __device__ __forceinline__ float bf_lo(unsigned w) { return __uint_as_float(w << 16); }
; __device__ __forceinline__ float bf_hi(unsigned w) { return __uint_as_float(w & 0xffff0000u); }
;     __device__ __forceinline__ void mid(f32x4 (&acc)[2][2][4][2], const pg8::Unit& u, int wr, int wc, int fr, int fq) const {
;     ...
;         for (int ai = 0; ai < 2; ++ai)
; #pragma unroll
;             for (int m = 0; m < 4; ++m)
; #pragma unroll
;                 for (int bj = 0; bj < 2; ++bj) {
;                     const size_t off = (size_t)(row0 + ai * 128 + m * 16) * D + c0 + bj * 8;
;                     const u32x4 a = *(const u32x4*)(sa + off), b = *(const u32x4*)(sb + off);
;                     f32x4 r0, r1;
;                     r0[0] = bf_lo(a.x) * __builtin_amdgcn_rcpf(bf_lo(b.x)); r0[1] = bf_hi(a.x) * __builtin_amdgcn_rcpf(bf_hi(b.x)); r0[2] = bf_lo(a.y) * __builtin_amdgcn_rcpf(bf_lo(b.y)); r0[3] = bf_hi(a.y) * __builtin_amdgcn_rcpf(bf_hi(b.y));
;                     r1[0] = bf_lo(a.z) * __builtin_amdgcn_rcpf(bf_lo(b.z)); r1[1] = bf_hi(a.z) * __builtin_amdgcn_rcpf(bf_hi(b.z)); r1[2] = bf_lo(a.w) * __builtin_amdgcn_rcpf(bf_lo(b.w)); r1[3] = bf_hi(a.w) * __builtin_amdgcn_rcpf(bf_hi(b.w));
;                     acc[ai][bj][m][0] *= r0; acc[ai][bj][m][1] *= r1;
;                     if ((m & 1) && bj == 1) asm volatile("" ::: "memory");
;                 }
	v_pk_mul_f32 v[80:81], v[80:81], v[160:161]
	v_pk_mul_f32 v[76:77], v[76:77], v[156:157]
	v_mov_b32_e32 v132, v240
	v_mov_b32_e32 v133, v241
	v_mov_b32_e32 v134, v242
	v_mov_b32_e32 v135, v243
	v_mov_b32_e32 v136, v244
	v_mov_b32_e32 v137, v245
	v_mov_b32_e32 v138, v246
	v_mov_b32_e32 v139, v247
	v_lshlrev_b32_e32 v158, 16, v132
	v_lshlrev_b32_e32 v0, 16, v136
	v_rcp_f32_e32 v156, v0
	v_and_b32_e32 v0, 0xffff0000, v136
	v_rcp_f32_e32 v157, v0
	v_lshlrev_b32_e32 v0, 16, v137
	v_rcp_f32_e32 v136, v0
	v_and_b32_e32 v0, 0xffff0000, v137
	v_rcp_f32_e32 v137, v0
	v_and_b32_e32 v159, 0xffff0000, v132
	v_lshlrev_b32_e32 v132, 16, v133
	v_and_b32_e32 v133, 0xffff0000, v133
	v_lshlrev_b32_e32 v0, 16, v138
	v_pk_mul_f32 v[132:133], v[136:137], v[132:133]
	v_rcp_f32_e32 v136, v0
	v_and_b32_e32 v0, 0xffff0000, v138
	v_rcp_f32_e32 v137, v0
	v_lshlrev_b32_e32 v0, 16, v139
	v_rcp_f32_e32 v138, v0
	v_and_b32_e32 v0, 0xffff0000, v139
	v_rcp_f32_e32 v139, v0
	v_pk_mul_f32 v[156:157], v[156:157], v[158:159]
	v_lshlrev_b32_e32 v158, 16, v134
	v_and_b32_e32 v159, 0xffff0000, v134
	v_pk_mul_f32 v[136:137], v[136:137], v[158:159]
	v_lshlrev_b32_e32 v134, 16, v135
	v_and_b32_e32 v135, 0xffff0000, v135
	v_pk_mul_f32 v[68:69], v[68:69], v[136:137]
	v_lshl_add_u64 v[136:137], v[2:3], 0, s[56:57]
	v_pk_mul_f32 v[134:135], v[138:139], v[134:135]
	v_lshl_add_u64 v[138:139], s[82:83], 0, v[136:137]
	v_lshl_add_u64 v[136:137], s[84:85], 0, v[136:137]
	v_pk_mul_f32 v[74:75], v[74:75], v[132:133]
	v_pk_mul_f32 v[72:73], v[72:73], v[156:157]
	v_pk_mul_f32 v[70:71], v[70:71], v[134:135]
	v_add_u32_e32 v165, 0x80000, v164
	global_load_dwordx4 v[172:175], v165, s[82:83]
	global_load_dwordx4 v[176:179], v165, s[84:85]
	global_load_dwordx4 v[180:183], v165, s[82:83] offset:16
	global_load_dwordx4 v[184:187], v165, s[84:85] offset:16
	v_add_u32_e32 v165, 0x90000, v164
	global_load_dwordx4 v[188:191], v165, s[82:83]
	global_load_dwordx4 v[192:195], v165, s[84:85]
	global_load_dwordx4 v[196:199], v165, s[82:83] offset:16
	global_load_dwordx4 v[212:215], v165, s[84:85] offset:16
	v_add_u32_e32 v165, 0xa0000, v164
	global_load_dwordx4 v[216:219], v165, s[82:83]
	global_load_dwordx4 v[220:223], v165, s[84:85]
	global_load_dwordx4 v[224:227], v165, s[82:83] offset:16
	global_load_dwordx4 v[228:231], v165, s[84:85] offset:16
	v_add_u32_e32 v165, 0xb0000, v164
	global_load_dwordx4 v[232:235], v165, s[82:83]
	global_load_dwordx4 v[236:239], v165, s[84:85]
	global_load_dwordx4 v[240:243], v165, s[82:83] offset:16
	global_load_dwordx4 v[244:247], v165, s[84:85] offset:16
	s_waitcnt vmcnt(0) lgkmcnt(0)
	v_mov_b32_e32 v132, v172
	v_mov_b32_e32 v133, v173
	v_mov_b32_e32 v134, v174
	v_mov_b32_e32 v135, v175
	v_mov_b32_e32 v156, v176
	v_mov_b32_e32 v157, v177
	v_mov_b32_e32 v158, v178
	v_mov_b32_e32 v159, v179
	v_lshlrev_b32_e32 v162, 16, v132
	v_lshlrev_b32_e32 v0, 16, v156
	v_rcp_f32_e32 v160, v0
	v_and_b32_e32 v0, 0xffff0000, v156
	v_rcp_f32_e32 v161, v0
	v_lshlrev_b32_e32 v0, 16, v157
	v_rcp_f32_e32 v156, v0
	v_and_b32_e32 v0, 0xffff0000, v157
	v_rcp_f32_e32 v157, v0
	v_and_b32_e32 v163, 0xffff0000, v132
	v_lshlrev_b32_e32 v132, 16, v133
	v_and_b32_e32 v133, 0xffff0000, v133
	v_lshlrev_b32_e32 v0, 16, v158
	v_pk_mul_f32 v[132:133], v[156:157], v[132:133]
	v_rcp_f32_e32 v156, v0
	v_and_b32_e32 v0, 0xffff0000, v158
	v_rcp_f32_e32 v157, v0
	v_lshlrev_b32_e32 v0, 16, v159
	v_rcp_f32_e32 v158, v0
	v_and_b32_e32 v0, 0xffff0000, v159
	v_rcp_f32_e32 v159, v0
	v_pk_mul_f32 v[160:161], v[160:161], v[162:163]
	v_lshlrev_b32_e32 v162, 16, v134
	v_and_b32_e32 v163, 0xffff0000, v134
	v_lshlrev_b32_e32 v134, 16, v135
	v_and_b32_e32 v135, 0xffff0000, v135
	v_pk_mul_f32 v[134:135], v[158:159], v[134:135]
	v_pk_mul_f32 v[66:67], v[66:67], v[132:133]
	v_pk_mul_f32 v[62:63], v[62:63], v[134:135]
	s_nop 0
	v_pk_mul_f32 v[156:157], v[156:157], v[162:163]
	v_pk_mul_f32 v[64:65], v[64:65], v[160:161]
	v_pk_mul_f32 v[60:61], v[60:61], v[156:157]
	v_mov_b32_e32 v132, v180
	v_mov_b32_e32 v133, v181
	v_mov_b32_e32 v134, v182
	v_mov_b32_e32 v135, v183
	v_mov_b32_e32 v136, v184
	v_mov_b32_e32 v137, v185
	v_mov_b32_e32 v138, v186
	v_mov_b32_e32 v139, v187
	v_lshlrev_b32_e32 v158, 16, v132
	v_lshlrev_b32_e32 v0, 16, v136
	v_rcp_f32_e32 v156, v0
	v_and_b32_e32 v0, 0xffff0000, v136
	v_rcp_f32_e32 v157, v0
	v_lshlrev_b32_e32 v0, 16, v137
	v_rcp_f32_e32 v136, v0
	v_and_b32_e32 v0, 0xffff0000, v137
	v_rcp_f32_e32 v137, v0
	v_and_b32_e32 v159, 0xffff0000, v132
	v_lshlrev_b32_e32 v132, 16, v133
	v_and_b32_e32 v133, 0xffff0000, v133
	v_lshlrev_b32_e32 v0, 16, v138
	v_pk_mul_f32 v[132:133], v[136:137], v[132:133]
	v_rcp_f32_e32 v136, v0
	v_and_b32_e32 v0, 0xffff0000, v138
	v_rcp_f32_e32 v137, v0
	v_lshlrev_b32_e32 v0, 16, v139
	v_rcp_f32_e32 v138, v0
	v_and_b32_e32 v0, 0xffff0000, v139
	v_rcp_f32_e32 v139, v0
	v_pk_mul_f32 v[156:157], v[156:157], v[158:159]
	v_lshlrev_b32_e32 v158, 16, v134
	v_and_b32_e32 v159, 0xffff0000, v134
	v_pk_mul_f32 v[136:137], v[136:137], v[158:159]
	v_lshlrev_b32_e32 v134, 16, v135
	v_and_b32_e32 v135, 0xffff0000, v135
	v_pk_mul_f32 v[52:53], v[52:53], v[136:137]
	v_lshl_add_u64 v[136:137], v[2:3], 0, s[36:37]
	v_pk_mul_f32 v[134:135], v[138:139], v[134:135]
	v_lshl_add_u64 v[138:139], s[82:83], 0, v[136:137]
	v_lshl_add_u64 v[136:137], s[84:85], 0, v[136:137]
	v_pk_mul_f32 v[58:59], v[58:59], v[132:133]
	v_pk_mul_f32 v[56:57], v[56:57], v[156:157]
	v_pk_mul_f32 v[54:55], v[54:55], v[134:135]
	s_mov_b64 s[36:37], 0xa0000
	v_mov_b32_e32 v132, v188
	v_mov_b32_e32 v133, v189
	v_mov_b32_e32 v134, v190
	v_mov_b32_e32 v135, v191
	v_mov_b32_e32 v156, v192
	v_mov_b32_e32 v157, v193
	v_mov_b32_e32 v158, v194
; __device__ __forceinline__ float bf_lo(unsigned w) { return __uint_as_float(w << 16); }
; __device__ __forceinline__ float bf_hi(unsigned w) { return __uint_as_float(w & 0xffff0000u); }
;     __device__ __forceinline__ void mid(f32x4 (&acc)[2][2][4][2], const pg8::Unit& u, int wr, int wc, int fr, int fq) const {
;     ...
;         for (int ai = 0; ai < 2; ++ai)
; #pragma unroll
;             for (int m = 0; m < 4; ++m)
; #pragma unroll
;                 for (int bj = 0; bj < 2; ++bj) {
;                     const size_t off = (size_t)(row0 + ai * 128 + m * 16) * D + c0 + bj * 8;
;                     const u32x4 a = *(const u32x4*)(sa + off), b = *(const u32x4*)(sb + off);
;                     f32x4 r0, r1;
;                     r0[0] = bf_lo(a.x) * __builtin_amdgcn_rcpf(bf_lo(b.x)); r0[1] = bf_hi(a.x) * __builtin_amdgcn_rcpf(bf_hi(b.x)); r0[2] = bf_lo(a.y) * __builtin_amdgcn_rcpf(bf_lo(b.y)); r0[3] = bf_hi(a.y) * __builtin_amdgcn_rcpf(bf_hi(b.y));
;                     r1[0] = bf_lo(a.z) * __builtin_amdgcn_rcpf(bf_lo(b.z)); r1[1] = bf_hi(a.z) * __builtin_amdgcn_rcpf(bf_hi(b.z)); r1[2] = bf_lo(a.w) * __builtin_amdgcn_rcpf(bf_lo(b.w)); r1[3] = bf_hi(a.w) * __builtin_amdgcn_rcpf(bf_hi(b.w));
;                     acc[ai][bj][m][0] *= r0; acc[ai][bj][m][1] *= r1;
;                     if ((m & 1) && bj == 1) asm volatile("" ::: "memory");
;                 }
	v_mov_b32_e32 v159, v195
	v_lshlrev_b32_e32 v162, 16, v132
	v_lshlrev_b32_e32 v0, 16, v156
	v_rcp_f32_e32 v160, v0
	v_and_b32_e32 v0, 0xffff0000, v156
	v_rcp_f32_e32 v161, v0
	v_lshlrev_b32_e32 v0, 16, v157
	v_rcp_f32_e32 v156, v0
	v_and_b32_e32 v0, 0xffff0000, v157
	v_rcp_f32_e32 v157, v0
	v_and_b32_e32 v163, 0xffff0000, v132
	v_lshlrev_b32_e32 v132, 16, v133
	v_and_b32_e32 v133, 0xffff0000, v133
	v_lshlrev_b32_e32 v0, 16, v158
	v_pk_mul_f32 v[132:133], v[156:157], v[132:133]
	v_rcp_f32_e32 v156, v0
	v_and_b32_e32 v0, 0xffff0000, v158
	v_rcp_f32_e32 v157, v0
	v_lshlrev_b32_e32 v0, 16, v159
	v_rcp_f32_e32 v158, v0
	v_and_b32_e32 v0, 0xffff0000, v159
	v_rcp_f32_e32 v159, v0
	v_pk_mul_f32 v[160:161], v[160:161], v[162:163]
	v_lshlrev_b32_e32 v162, 16, v134
	v_and_b32_e32 v163, 0xffff0000, v134
	v_lshlrev_b32_e32 v134, 16, v135
	v_and_b32_e32 v135, 0xffff0000, v135
	v_pk_mul_f32 v[134:135], v[158:159], v[134:135]
	v_pk_mul_f32 v[50:51], v[50:51], v[132:133]
	v_pk_mul_f32 v[46:47], v[46:47], v[134:135]
	s_nop 0
	v_pk_mul_f32 v[156:157], v[156:157], v[162:163]
	v_pk_mul_f32 v[48:49], v[48:49], v[160:161]
	v_pk_mul_f32 v[44:45], v[44:45], v[156:157]
	v_mov_b32_e32 v132, v196
	v_mov_b32_e32 v133, v197
	v_mov_b32_e32 v134, v198
	v_mov_b32_e32 v135, v199
	v_mov_b32_e32 v136, v212
	v_mov_b32_e32 v137, v213
	v_mov_b32_e32 v138, v214
	v_mov_b32_e32 v139, v215
	v_lshlrev_b32_e32 v158, 16, v132
	v_lshlrev_b32_e32 v0, 16, v136
	v_rcp_f32_e32 v156, v0
	v_and_b32_e32 v0, 0xffff0000, v136
	v_rcp_f32_e32 v157, v0
	v_lshlrev_b32_e32 v0, 16, v137
	v_rcp_f32_e32 v136, v0
	v_and_b32_e32 v0, 0xffff0000, v137
	v_rcp_f32_e32 v137, v0
	v_and_b32_e32 v159, 0xffff0000, v132
	v_lshlrev_b32_e32 v132, 16, v133
	v_and_b32_e32 v133, 0xffff0000, v133
	v_lshlrev_b32_e32 v0, 16, v138
	v_pk_mul_f32 v[132:133], v[136:137], v[132:133]
	v_rcp_f32_e32 v136, v0
	v_and_b32_e32 v0, 0xffff0000, v138
	v_rcp_f32_e32 v137, v0
	v_lshlrev_b32_e32 v0, 16, v139
	v_rcp_f32_e32 v138, v0
	v_and_b32_e32 v0, 0xffff0000, v139
	v_rcp_f32_e32 v139, v0
	v_pk_mul_f32 v[156:157], v[156:157], v[158:159]
	v_lshlrev_b32_e32 v158, 16, v134
	v_and_b32_e32 v159, 0xffff0000, v134
	v_pk_mul_f32 v[136:137], v[136:137], v[158:159]
	v_lshlrev_b32_e32 v134, 16, v135
	v_and_b32_e32 v135, 0xffff0000, v135
	v_pk_mul_f32 v[36:37], v[36:37], v[136:137]
	v_lshl_add_u64 v[136:137], v[2:3], 0, s[36:37]
	v_pk_mul_f32 v[134:135], v[138:139], v[134:135]
	v_lshl_add_u64 v[138:139], s[82:83], 0, v[136:137]
	v_lshl_add_u64 v[136:137], s[84:85], 0, v[136:137]
	v_pk_mul_f32 v[42:43], v[42:43], v[132:133]
	v_pk_mul_f32 v[40:41], v[40:41], v[156:157]
	v_pk_mul_f32 v[38:39], v[38:39], v[134:135]
	s_mov_b64 s[36:37], 0xb0000
	v_lshl_add_u64 v[2:3], v[2:3], 0, s[36:37]
	v_mov_b32_e32 v132, v216
	v_mov_b32_e32 v133, v217
	v_mov_b32_e32 v134, v218
	v_mov_b32_e32 v135, v219
	v_mov_b32_e32 v156, v220
	v_mov_b32_e32 v157, v221
	v_mov_b32_e32 v158, v222
	v_mov_b32_e32 v159, v223
	v_lshlrev_b32_e32 v162, 16, v132
	v_lshlrev_b32_e32 v0, 16, v156
	v_rcp_f32_e32 v160, v0
	v_and_b32_e32 v0, 0xffff0000, v156
	v_rcp_f32_e32 v161, v0
	v_lshlrev_b32_e32 v0, 16, v157
	v_rcp_f32_e32 v156, v0
	v_and_b32_e32 v0, 0xffff0000, v157
	v_rcp_f32_e32 v157, v0
	v_and_b32_e32 v163, 0xffff0000, v132
	v_lshlrev_b32_e32 v132, 16, v133
	v_and_b32_e32 v133, 0xffff0000, v133
	v_lshlrev_b32_e32 v0, 16, v158
	v_pk_mul_f32 v[132:133], v[156:157], v[132:133]
	v_rcp_f32_e32 v156, v0
	v_and_b32_e32 v0, 0xffff0000, v158
	v_rcp_f32_e32 v157, v0
	v_lshlrev_b32_e32 v0, 16, v159
	v_rcp_f32_e32 v158, v0
	v_and_b32_e32 v0, 0xffff0000, v159
	v_rcp_f32_e32 v159, v0
	v_pk_mul_f32 v[160:161], v[160:161], v[162:163]
	v_lshlrev_b32_e32 v162, 16, v134
	v_and_b32_e32 v163, 0xffff0000, v134
	v_lshlrev_b32_e32 v134, 16, v135
	v_and_b32_e32 v135, 0xffff0000, v135
	v_pk_mul_f32 v[134:135], v[158:159], v[134:135]
	v_pk_mul_f32 v[34:35], v[34:35], v[132:133]
	v_pk_mul_f32 v[30:31], v[30:31], v[134:135]
	s_nop 0
	v_pk_mul_f32 v[156:157], v[156:157], v[162:163]
	v_pk_mul_f32 v[32:33], v[32:33], v[160:161]
	v_pk_mul_f32 v[28:29], v[28:29], v[156:157]
; __device__ __forceinline__ float bf_lo(unsigned w) { return __uint_as_float(w << 16); }
; __device__ __forceinline__ float bf_hi(unsigned w) { return __uint_as_float(w & 0xffff0000u); }
;     __device__ __forceinline__ void mid(f32x4 (&acc)[2][2][4][2], const pg8::Unit& u, int wr, int wc, int fr, int fq) const {
;     ...
;         for (int ai = 0; ai < 2; ++ai)
; #pragma unroll
;             for (int m = 0; m < 4; ++m)
; #pragma unroll
;                 for (int bj = 0; bj < 2; ++bj) {
;                     const size_t off = (size_t)(row0 + ai * 128 + m * 16) * D + c0 + bj * 8;
;                     const u32x4 a = *(const u32x4*)(sa + off), b = *(const u32x4*)(sb + off);
;                     f32x4 r0, r1;
;                     r0[0] = bf_lo(a.x) * __builtin_amdgcn_rcpf(bf_lo(b.x)); r0[1] = bf_hi(a.x) * __builtin_amdgcn_rcpf(bf_hi(b.x)); r0[2] = bf_lo(a.y) * __builtin_amdgcn_rcpf(bf_lo(b.y)); r0[3] = bf_hi(a.y) * __builtin_amdgcn_rcpf(bf_hi(b.y));
;                     r1[0] = bf_lo(a.z) * __builtin_amdgcn_rcpf(bf_lo(b.z)); r1[1] = bf_hi(a.z) * __builtin_amdgcn_rcpf(bf_hi(b.z)); r1[2] = bf_lo(a.w) * __builtin_amdgcn_rcpf(bf_lo(b.w)); r1[3] = bf_hi(a.w) * __builtin_amdgcn_rcpf(bf_hi(b.w));
;                     acc[ai][bj][m][0] *= r0; acc[ai][bj][m][1] *= r1;
;                     if ((m & 1) && bj == 1) asm volatile("" ::: "memory");
;                 }
	v_mov_b32_e32 v132, v224
	v_mov_b32_e32 v133, v225
	v_mov_b32_e32 v134, v226
	v_mov_b32_e32 v135, v227
	v_mov_b32_e32 v136, v228
	v_mov_b32_e32 v137, v229
	v_mov_b32_e32 v138, v230
	v_mov_b32_e32 v139, v231
	v_lshlrev_b32_e32 v158, 16, v132
	v_lshlrev_b32_e32 v0, 16, v136
	v_rcp_f32_e32 v156, v0
	v_and_b32_e32 v0, 0xffff0000, v136
	v_rcp_f32_e32 v157, v0
	v_lshlrev_b32_e32 v0, 16, v137
	v_rcp_f32_e32 v136, v0
	v_and_b32_e32 v0, 0xffff0000, v137
	v_rcp_f32_e32 v137, v0
	v_and_b32_e32 v159, 0xffff0000, v132
	v_lshlrev_b32_e32 v132, 16, v133
	v_and_b32_e32 v133, 0xffff0000, v133
	v_lshlrev_b32_e32 v0, 16, v138
	v_pk_mul_f32 v[132:133], v[136:137], v[132:133]
	v_rcp_f32_e32 v136, v0
	v_and_b32_e32 v0, 0xffff0000, v138
	v_rcp_f32_e32 v137, v0
	v_lshlrev_b32_e32 v0, 16, v139
	v_rcp_f32_e32 v138, v0
	v_and_b32_e32 v0, 0xffff0000, v139
	v_rcp_f32_e32 v139, v0
	v_pk_mul_f32 v[156:157], v[156:157], v[158:159]
	v_lshlrev_b32_e32 v158, 16, v134
	v_and_b32_e32 v159, 0xffff0000, v134
	v_lshlrev_b32_e32 v134, 16, v135
	v_and_b32_e32 v135, 0xffff0000, v135
	v_pk_mul_f32 v[136:137], v[136:137], v[158:159]
	v_pk_mul_f32 v[134:135], v[138:139], v[134:135]
	v_pk_mul_f32 v[24:25], v[24:25], v[156:157]
	v_lshl_add_u64 v[156:157], s[82:83], 0, v[2:3]
	v_lshl_add_u64 v[2:3], s[84:85], 0, v[2:3]
	v_pk_mul_f32 v[26:27], v[26:27], v[132:133]
	v_pk_mul_f32 v[22:23], v[22:23], v[134:135]
	v_pk_mul_f32 v[20:21], v[20:21], v[136:137]
	v_mov_b32_e32 v132, v232
	v_mov_b32_e32 v133, v233
	v_mov_b32_e32 v134, v234
	v_mov_b32_e32 v135, v235
	v_mov_b32_e32 v136, v236
	v_mov_b32_e32 v137, v237
	v_mov_b32_e32 v138, v238
	v_mov_b32_e32 v139, v239
	v_lshlrev_b32_e32 v160, 16, v132
	v_lshlrev_b32_e32 v0, 16, v136
	v_rcp_f32_e32 v158, v0
	v_and_b32_e32 v0, 0xffff0000, v136
	v_rcp_f32_e32 v159, v0
	v_lshlrev_b32_e32 v0, 16, v137
	v_rcp_f32_e32 v136, v0
	v_and_b32_e32 v0, 0xffff0000, v137
	v_rcp_f32_e32 v137, v0
	v_and_b32_e32 v161, 0xffff0000, v132
	v_lshlrev_b32_e32 v132, 16, v133
	v_and_b32_e32 v133, 0xffff0000, v133
	v_lshlrev_b32_e32 v0, 16, v138
	v_pk_mul_f32 v[132:133], v[136:137], v[132:133]
	v_rcp_f32_e32 v136, v0
	v_and_b32_e32 v0, 0xffff0000, v138
	v_rcp_f32_e32 v137, v0
	v_lshlrev_b32_e32 v0, 16, v139
	v_rcp_f32_e32 v138, v0
	v_and_b32_e32 v0, 0xffff0000, v139
	v_rcp_f32_e32 v139, v0
	v_pk_mul_f32 v[158:159], v[158:159], v[160:161]
	v_lshlrev_b32_e32 v160, 16, v134
	v_and_b32_e32 v161, 0xffff0000, v134
	v_lshlrev_b32_e32 v134, 16, v135
	v_and_b32_e32 v135, 0xffff0000, v135
	v_pk_mul_f32 v[136:137], v[136:137], v[160:161]
	v_pk_mul_f32 v[134:135], v[138:139], v[134:135]
	v_pk_mul_f32 v[18:19], v[18:19], v[132:133]
	v_pk_mul_f32 v[14:15], v[14:15], v[134:135]
	v_pk_mul_f32 v[12:13], v[12:13], v[136:137]
	v_pk_mul_f32 v[16:17], v[16:17], v[158:159]
	v_mov_b32_e32 v132, v240
	v_mov_b32_e32 v133, v241
	v_mov_b32_e32 v134, v242
	v_mov_b32_e32 v135, v243
	v_mov_b32_e32 v136, v244
	v_mov_b32_e32 v137, v245
	v_mov_b32_e32 v138, v246
	v_mov_b32_e32 v139, v247
	v_lshlrev_b32_e32 v156, 16, v132
	v_lshlrev_b32_e32 v0, 16, v136
	v_rcp_f32_e32 v2, v0
	v_and_b32_e32 v0, 0xffff0000, v136
	v_rcp_f32_e32 v3, v0
	v_lshlrev_b32_e32 v0, 16, v137
	v_rcp_f32_e32 v136, v0
	v_and_b32_e32 v0, 0xffff0000, v137
	v_rcp_f32_e32 v137, v0
	v_and_b32_e32 v157, 0xffff0000, v132
	v_lshlrev_b32_e32 v132, 16, v133
	v_and_b32_e32 v133, 0xffff0000, v133
	v_lshlrev_b32_e32 v0, 16, v138
	v_pk_mul_f32 v[132:133], v[136:137], v[132:133]
	v_rcp_f32_e32 v136, v0
	v_and_b32_e32 v0, 0xffff0000, v138
	v_rcp_f32_e32 v137, v0
	v_lshlrev_b32_e32 v0, 16, v139
	v_rcp_f32_e32 v138, v0
	v_and_b32_e32 v0, 0xffff0000, v139
	v_rcp_f32_e32 v139, v0
	v_pk_mul_f32 v[2:3], v[2:3], v[156:157]
	v_lshlrev_b32_e32 v156, 16, v134
	v_and_b32_e32 v157, 0xffff0000, v134
	v_lshlrev_b32_e32 v134, 16, v135
	v_and_b32_e32 v135, 0xffff0000, v135
	v_pk_mul_f32 v[136:137], v[136:137], v[156:157]
	v_pk_mul_f32 v[134:135], v[138:139], v[134:135]
	v_pk_mul_f32 v[10:11], v[10:11], v[132:133]
	v_pk_mul_f32 v[8:9], v[8:9], v[2:3]
	v_pk_mul_f32 v[6:7], v[6:7], v[134:135]
	v_pk_mul_f32 v[4:5], v[4:5], v[136:137]
	s_branch .LBB0_454

; #define LAS __attribute__((address_space(3)))
; __device__ __forceinline__ float bf_lo(unsigned w) { return __uint_as_float(w << 16); }
; __device__ __forceinline__ float bf_hi(unsigned w) { return __uint_as_float(w & 0xffff0000u); }
; __device__ __forceinline__ u32x4 pack8(const f32x4 a, const f32x4 b) { u32x4 w; w.x = cvt_pk_bf16(a[0], a[1]); w.y = cvt_pk_bf16(a[2], a[3]); w.z = cvt_pk_bf16(b[0], b[1]); w.w = cvt_pk_bf16(b[2], b[3]); return w; }
;     __device__ __forceinline__ void operator()(const f32x4 (&acc)[2][2][4][2], const pg8::Unit& u, int wr, int wc, int fr, int fq, LAS unsigned char*, int) const {
;         const int row0 = u.pm * 256 + wr * 64 + fr, c0 = u.pn * 256 + wc * 64 + 16 * fq;
; #pragma unroll
;         for (int ai = 0; ai < 2; ++ai)
; #pragma unroll
;             for (int m = 0; m < 4; ++m)
; #pragma unroll
;                 for (int bj = 0; bj < 2; ++bj) {
;                     const size_t off = (size_t)(row0 + ai * 128 + m * 16) * D + c0 + bj * 8;
;                     const u32x4 b = *(const u32x4*)(sb + off);
;                     f32x4 v0 = acc[ai][bj][m][0], v1 = acc[ai][bj][m][1];
;                     v0[0] *= bf_lo(b.x); v0[1] *= bf_hi(b.x); v0[2] *= bf_lo(b.y); v0[3] *= bf_hi(b.y);
;                     v1[0] *= bf_lo(b.z); v1[1] *= bf_hi(b.z); v1[2] *= bf_lo(b.w); v1[3] *= bf_hi(b.w);
;                     *(u32x4*)(o + off) = pack8(v0, v1);
;                 }
.LBB0_469:
	v_ashrrev_i32_e32 v151, 31, v150
	v_ashrrev_i32_e32 v149, 31, v148
	v_lshlrev_b64 v[2:3], 11, v[150:151]
	v_lshl_add_u64 v[2:3], v[2:3], 0, v[148:149]
	v_lshlrev_b64 v[2:3], 1, v[2:3]
	v_lshl_add_u64 v[132:133], s[84:85], 0, v[2:3]
	v_lshlrev_b32_e32 v164, 11, v150
	v_add_lshl_u32 v164, v164, v148, 1
	v_mov_b32_e32 v165, v164
	global_load_dwordx4 v[172:175], v165, s[84:85]
	global_load_dwordx4 v[176:179], v165, s[84:85] offset:16
	v_add_u32_e32 v165, 0x10000, v164
	global_load_dwordx4 v[180:183], v165, s[84:85]
	global_load_dwordx4 v[184:187], v165, s[84:85] offset:16
	v_add_u32_e32 v165, 0x20000, v164
	global_load_dwordx4 v[188:191], v165, s[84:85]
	global_load_dwordx4 v[192:195], v165, s[84:85] offset:16
	v_add_u32_e32 v165, 0x30000, v164
	global_load_dwordx4 v[196:199], v165, s[84:85]
	global_load_dwordx4 v[212:215], v165, s[84:85] offset:16
	v_add_u32_e32 v165, 0x80000, v164
	global_load_dwordx4 v[216:219], v165, s[84:85]
	global_load_dwordx4 v[220:223], v165, s[84:85] offset:16
	v_add_u32_e32 v165, 0x90000, v164
	global_load_dwordx4 v[224:227], v165, s[84:85]
	global_load_dwordx4 v[228:231], v165, s[84:85] offset:16
	v_add_u32_e32 v165, 0xa0000, v164
	global_load_dwordx4 v[232:235], v165, s[84:85]
	global_load_dwordx4 v[236:239], v165, s[84:85] offset:16
	v_add_u32_e32 v165, 0xb0000, v164
	global_load_dwordx4 v[240:243], v165, s[84:85]
	global_load_dwordx4 v[244:247], v165, s[84:85] offset:16
	v_or_b32_e32 v136, 16, v2
	v_mov_b32_e32 v137, v3
	v_lshl_add_u64 v[138:139], s[84:85], 0, v[136:137]
	v_readlane_b32 s22, v251, 43
	v_readlane_b32 s23, v251, 44
	s_mov_b64 s[20:21], 0x80010
	s_andn2_b64 vcc, exec, s[16:17]
	v_lshl_add_u64 v[136:137], s[22:23], 0, v[136:137]
	s_mov_b64 s[16:17], -1
	s_waitcnt vmcnt(0) lgkmcnt(0)
	v_mov_b32_e32 v132, v172
	v_mov_b32_e32 v133, v173
	v_mov_b32_e32 v134, v174
	v_mov_b32_e32 v135, v175
	v_lshlrev_b32_e32 v0, 16, v132
	v_and_b32_e32 v132, 0xffff0000, v132
	v_lshlrev_b32_e32 v151, 16, v133
	v_and_b32_e32 v133, 0xffff0000, v133
	v_lshlrev_b32_e32 v156, 16, v134
	v_lshlrev_b32_e32 v157, 16, v135
	v_and_b32_e32 v135, 0xffff0000, v135
	v_and_b32_e32 v134, 0xffff0000, v134
	v_mul_f32_e32 v0, v128, v0
	v_mul_f32_e32 v128, v129, v132
	v_mul_f32_e32 v129, v130, v151
	v_mul_f32_e32 v130, v131, v133
	v_mul_f32_e32 v131, v124, v156
	v_mul_f32_e32 v127, v127, v135
	v_mul_f32_e32 v132, v125, v134
	v_mul_f32_e32 v133, v126, v157
	v_cvt_pk_bf16_f32 v124, v0, v128
	v_cvt_pk_bf16_f32 v125, v129, v130
	v_cvt_pk_bf16_f32 v126, v131, v132
	v_cvt_pk_bf16_f32 v127, v133, v127
	v_or_b32_e32 v132, 16, v150
	v_ashrrev_i32_e32 v133, 31, v132
	v_lshlrev_b64 v[132:133], 11, v[132:133]
	v_lshl_add_u64 v[134:135], s[22:23], 0, v[2:3]
	v_lshl_add_u64 v[132:133], v[132:133], 0, v[148:149]
	global_store_dwordx4 v[134:135], v[124:127], off
	v_lshlrev_b64 v[132:133], 1, v[132:133]
	v_lshl_add_u64 v[138:139], s[84:85], 0, v[132:133]
	s_waitcnt lgkmcnt(0)
	v_mov_b32_e32 v128, v176
	v_mov_b32_e32 v129, v177
	v_mov_b32_e32 v130, v178
	v_mov_b32_e32 v131, v179
	v_lshlrev_b32_e32 v0, 16, v128
	v_and_b32_e32 v124, 0xffff0000, v128
	v_lshlrev_b32_e32 v127, 16, v130
	v_and_b32_e32 v128, 0xffff0000, v130
	v_and_b32_e32 v130, 0xffff0000, v131
	v_lshlrev_b32_e32 v125, 16, v129
	v_and_b32_e32 v126, 0xffff0000, v129
	v_lshlrev_b32_e32 v129, 16, v131
	v_mul_f32_e32 v119, v119, v130
	v_mul_f32_e32 v0, v120, v0
	v_mul_f32_e32 v120, v121, v124
	v_mul_f32_e32 v121, v122, v125
	v_mul_f32_e32 v122, v123, v126
	v_mul_f32_e32 v123, v116, v127
	v_mul_f32_e32 v124, v117, v128
	v_mul_f32_e32 v125, v118, v129
	v_cvt_pk_bf16_f32 v116, v0, v120
	v_cvt_pk_bf16_f32 v117, v121, v122
	v_cvt_pk_bf16_f32 v118, v123, v124
	v_cvt_pk_bf16_f32 v119, v125, v119
	global_store_dwordx4 v[136:137], v[116:119], off
	v_lshl_add_u64 v[120:121], s[22:23], 0, v[132:133]
	v_or_b32_e32 v132, 16, v132
	v_lshl_add_u64 v[122:123], s[84:85], 0, v[132:133]
	s_waitcnt lgkmcnt(0)
	v_mov_b32_e32 v116, v180
	v_mov_b32_e32 v117, v181
	v_mov_b32_e32 v118, v182
	v_mov_b32_e32 v119, v183
	v_lshlrev_b32_e32 v0, 16, v116
	v_and_b32_e32 v116, 0xffff0000, v116
	v_lshlrev_b32_e32 v124, 16, v117
	v_and_b32_e32 v117, 0xffff0000, v117
	v_lshlrev_b32_e32 v125, 16, v118
	v_lshlrev_b32_e32 v126, 16, v119
	v_and_b32_e32 v119, 0xffff0000, v119
	v_and_b32_e32 v118, 0xffff0000, v118
	v_mul_f32_e32 v0, v112, v0
	v_mul_f32_e32 v112, v113, v116
	v_mul_f32_e32 v113, v114, v124
	v_mul_f32_e32 v114, v115, v117
	v_mul_f32_e32 v115, v108, v125
	v_mul_f32_e32 v111, v111, v119
	v_mul_f32_e32 v116, v109, v118
	v_mul_f32_e32 v117, v110, v126
	v_cvt_pk_bf16_f32 v108, v0, v112
	v_cvt_pk_bf16_f32 v109, v113, v114
	v_cvt_pk_bf16_f32 v110, v115, v116
	v_cvt_pk_bf16_f32 v111, v117, v111
	v_or_b32_e32 v116, 32, v150
	v_ashrrev_i32_e32 v117, 31, v116
	v_lshlrev_b64 v[116:117], 11, v[116:117]
	v_lshl_add_u64 v[116:117], v[116:117], 0, v[148:149]
	global_store_dwordx4 v[120:121], v[108:111], off
	v_lshlrev_b64 v[116:117], 1, v[116:117]
	v_lshl_add_u64 v[122:123], s[22:23], 0, v[132:133]
	v_lshl_add_u64 v[118:119], s[84:85], 0, v[116:117]
	s_waitcnt lgkmcnt(0)
	v_mov_b32_e32 v112, v184
	v_mov_b32_e32 v113, v185
	v_mov_b32_e32 v114, v186
	v_mov_b32_e32 v115, v187
	v_lshlrev_b32_e32 v0, 16, v112
	v_and_b32_e32 v108, 0xffff0000, v112
	v_lshlrev_b32_e32 v111, 16, v114
	v_and_b32_e32 v112, 0xffff0000, v114
	v_and_b32_e32 v114, 0xffff0000, v115
	v_lshlrev_b32_e32 v109, 16, v113
	v_and_b32_e32 v110, 0xffff0000, v113
	v_lshlrev_b32_e32 v113, 16, v115
	v_mul_f32_e32 v103, v103, v114
	v_mul_f32_e32 v0, v104, v0
	v_mul_f32_e32 v104, v105, v108
	v_mul_f32_e32 v105, v106, v109
	v_mul_f32_e32 v106, v107, v110
	v_mul_f32_e32 v107, v100, v111
	v_mul_f32_e32 v108, v101, v112
	v_mul_f32_e32 v109, v102, v113
	v_cvt_pk_bf16_f32 v100, v0, v104
	v_cvt_pk_bf16_f32 v101, v105, v106
	v_cvt_pk_bf16_f32 v102, v107, v108
	v_cvt_pk_bf16_f32 v103, v109, v103
	global_store_dwordx4 v[122:123], v[100:103], off
	v_lshl_add_u64 v[104:105], s[22:23], 0, v[116:117]
	v_or_b32_e32 v116, 16, v116
	v_lshl_add_u64 v[106:107], s[84:85], 0, v[116:117]
	s_waitcnt lgkmcnt(0)
; __device__ __forceinline__ float bf_lo(unsigned w) { return __uint_as_float(w << 16); }
; __device__ __forceinline__ float bf_hi(unsigned w) { return __uint_as_float(w & 0xffff0000u); }
; __device__ __forceinline__ u32x4 pack8(const f32x4 a, const f32x4 b) { u32x4 w; w.x = cvt_pk_bf16(a[0], a[1]); w.y = cvt_pk_bf16(a[2], a[3]); w.z = cvt_pk_bf16(b[0], b[1]); w.w = cvt_pk_bf16(b[2], b[3]); return w; }
;     __device__ __forceinline__ void operator()(const f32x4 (&acc)[2][2][4][2], const pg8::Unit& u, int wr, int wc, int fr, int fq, LAS unsigned char*, int) const {
;     ...
;                 for (int bj = 0; bj < 2; ++bj) {
;                     const size_t off = (size_t)(row0 + ai * 128 + m * 16) * D + c0 + bj * 8;
;                     const u32x4 b = *(const u32x4*)(sb + off);
;                     f32x4 v0 = acc[ai][bj][m][0], v1 = acc[ai][bj][m][1];
;                     v0[0] *= bf_lo(b.x); v0[1] *= bf_hi(b.x); v0[2] *= bf_lo(b.y); v0[3] *= bf_hi(b.y);
;                     v1[0] *= bf_lo(b.z); v1[1] *= bf_hi(b.z); v1[2] *= bf_lo(b.w); v1[3] *= bf_hi(b.w);
;                     *(u32x4*)(o + off) = pack8(v0, v1);
;                 }
	v_mov_b32_e32 v100, v188
	v_mov_b32_e32 v101, v189
	v_mov_b32_e32 v102, v190
	v_mov_b32_e32 v103, v191
	v_lshlrev_b32_e32 v0, 16, v100
	v_and_b32_e32 v100, 0xffff0000, v100
	v_lshlrev_b32_e32 v108, 16, v101
	v_and_b32_e32 v101, 0xffff0000, v101
	v_lshlrev_b32_e32 v109, 16, v102
	v_lshlrev_b32_e32 v110, 16, v103
	v_and_b32_e32 v103, 0xffff0000, v103
	v_and_b32_e32 v102, 0xffff0000, v102
	v_mul_f32_e32 v0, v96, v0
	v_mul_f32_e32 v96, v97, v100
	v_mul_f32_e32 v97, v98, v108
	v_mul_f32_e32 v98, v99, v101
	v_mul_f32_e32 v99, v92, v109
	v_mul_f32_e32 v95, v95, v103
	v_mul_f32_e32 v100, v93, v102
	v_mul_f32_e32 v101, v94, v110
	v_cvt_pk_bf16_f32 v92, v0, v96
	v_cvt_pk_bf16_f32 v93, v97, v98
	v_cvt_pk_bf16_f32 v94, v99, v100
	v_cvt_pk_bf16_f32 v95, v101, v95
	v_or_b32_e32 v100, 48, v150
	v_ashrrev_i32_e32 v101, 31, v100
	v_lshlrev_b64 v[100:101], 11, v[100:101]
	v_lshl_add_u64 v[100:101], v[100:101], 0, v[148:149]
	global_store_dwordx4 v[104:105], v[92:95], off
	v_lshlrev_b64 v[100:101], 1, v[100:101]
	v_lshl_add_u64 v[106:107], s[22:23], 0, v[116:117]
	v_lshl_add_u64 v[102:103], s[84:85], 0, v[100:101]
	s_waitcnt lgkmcnt(0)
	v_mov_b32_e32 v96, v192
	v_mov_b32_e32 v97, v193
	v_mov_b32_e32 v98, v194
	v_mov_b32_e32 v99, v195
	v_lshlrev_b32_e32 v0, 16, v96
	v_and_b32_e32 v92, 0xffff0000, v96
	v_lshlrev_b32_e32 v95, 16, v98
	v_and_b32_e32 v96, 0xffff0000, v98
	v_and_b32_e32 v98, 0xffff0000, v99
	v_lshlrev_b32_e32 v93, 16, v97
	v_and_b32_e32 v94, 0xffff0000, v97
	v_lshlrev_b32_e32 v97, 16, v99
	v_mul_f32_e32 v87, v87, v98
	v_mul_f32_e32 v0, v88, v0
	v_mul_f32_e32 v88, v89, v92
	v_mul_f32_e32 v89, v90, v93
	v_mul_f32_e32 v90, v91, v94
	v_mul_f32_e32 v91, v84, v95
	v_mul_f32_e32 v92, v85, v96
	v_mul_f32_e32 v93, v86, v97
	v_cvt_pk_bf16_f32 v84, v0, v88
	v_cvt_pk_bf16_f32 v85, v89, v90
	v_cvt_pk_bf16_f32 v86, v91, v92
	v_cvt_pk_bf16_f32 v87, v93, v87
	global_store_dwordx4 v[106:107], v[84:87], off
	v_lshl_add_u64 v[88:89], s[22:23], 0, v[100:101]
	v_or_b32_e32 v100, 16, v100
	v_lshl_add_u64 v[90:91], s[84:85], 0, v[100:101]
	s_waitcnt lgkmcnt(0)
	v_mov_b32_e32 v84, v196
	v_mov_b32_e32 v85, v197
	v_mov_b32_e32 v86, v198
	v_mov_b32_e32 v87, v199
	v_lshlrev_b32_e32 v0, 16, v84
	v_and_b32_e32 v84, 0xffff0000, v84
	v_lshlrev_b32_e32 v92, 16, v85
	v_and_b32_e32 v85, 0xffff0000, v85
	v_lshlrev_b32_e32 v93, 16, v86
	v_lshlrev_b32_e32 v94, 16, v87
	v_and_b32_e32 v87, 0xffff0000, v87
	v_and_b32_e32 v86, 0xffff0000, v86
	v_mul_f32_e32 v0, v80, v0
	v_mul_f32_e32 v80, v81, v84
	v_mul_f32_e32 v81, v82, v92
	v_mul_f32_e32 v82, v83, v85
	v_mul_f32_e32 v83, v76, v93
	v_mul_f32_e32 v79, v79, v87
	v_mul_f32_e32 v84, v77, v86
	v_mul_f32_e32 v85, v78, v94
	v_cvt_pk_bf16_f32 v76, v0, v80
	v_cvt_pk_bf16_f32 v77, v81, v82
	v_cvt_pk_bf16_f32 v78, v83, v84
	v_cvt_pk_bf16_f32 v79, v85, v79
	v_lshl_add_u64 v[84:85], v[2:3], 0, s[56:57]
	global_store_dwordx4 v[88:89], v[76:79], off
	v_lshl_add_u64 v[90:91], s[22:23], 0, v[100:101]
	v_lshl_add_u64 v[86:87], s[84:85], 0, v[84:85]
	s_waitcnt lgkmcnt(0)
	v_mov_b32_e32 v80, v212
	v_mov_b32_e32 v81, v213
	v_mov_b32_e32 v82, v214
	v_mov_b32_e32 v83, v215
	v_lshlrev_b32_e32 v0, 16, v80
	v_and_b32_e32 v76, 0xffff0000, v80
	v_lshlrev_b32_e32 v79, 16, v82
	v_and_b32_e32 v80, 0xffff0000, v82
	v_and_b32_e32 v82, 0xffff0000, v83
	v_lshlrev_b32_e32 v77, 16, v81
	v_and_b32_e32 v78, 0xffff0000, v81
	v_lshlrev_b32_e32 v81, 16, v83
	v_mul_f32_e32 v71, v71, v82
	v_mul_f32_e32 v0, v72, v0
	v_mul_f32_e32 v72, v73, v76
	v_mul_f32_e32 v73, v74, v77
	v_mul_f32_e32 v74, v75, v78
	v_mul_f32_e32 v75, v68, v79
	v_mul_f32_e32 v76, v69, v80
	v_mul_f32_e32 v77, v70, v81
	v_cvt_pk_bf16_f32 v68, v0, v72
	v_cvt_pk_bf16_f32 v69, v73, v74
	v_cvt_pk_bf16_f32 v70, v75, v76
	v_cvt_pk_bf16_f32 v71, v77, v71
	global_store_dwordx4 v[90:91], v[68:71], off
	v_lshl_add_u64 v[72:73], v[2:3], 0, s[20:21]
	v_lshl_add_u64 v[74:75], s[84:85], 0, v[72:73]
	s_mov_b64 s[20:21], 0x90000
	v_lshl_add_u64 v[72:73], s[22:23], 0, v[72:73]
	s_waitcnt lgkmcnt(0)
	v_mov_b32_e32 v68, v216
	v_mov_b32_e32 v69, v217
	v_mov_b32_e32 v70, v218
	v_mov_b32_e32 v71, v219
	v_lshlrev_b32_e32 v0, 16, v68
	v_and_b32_e32 v68, 0xffff0000, v68
	v_lshlrev_b32_e32 v76, 16, v69
	v_and_b32_e32 v69, 0xffff0000, v69
	v_lshlrev_b32_e32 v77, 16, v70
	v_lshlrev_b32_e32 v78, 16, v71
	v_and_b32_e32 v71, 0xffff0000, v71
	v_and_b32_e32 v70, 0xffff0000, v70
	v_mul_f32_e32 v0, v64, v0
	v_mul_f32_e32 v64, v65, v68
	v_mul_f32_e32 v65, v66, v76
	v_mul_f32_e32 v66, v67, v69
	v_mul_f32_e32 v67, v60, v77
	v_mul_f32_e32 v63, v63, v71
	v_mul_f32_e32 v68, v61, v70
	v_mul_f32_e32 v69, v62, v78
	v_cvt_pk_bf16_f32 v60, v0, v64
	v_cvt_pk_bf16_f32 v61, v65, v66
	v_cvt_pk_bf16_f32 v62, v67, v68
	v_cvt_pk_bf16_f32 v63, v69, v63
	v_lshl_add_u64 v[70:71], s[22:23], 0, v[84:85]
	global_store_dwordx4 v[70:71], v[60:63], off
	v_lshl_add_u64 v[68:69], v[2:3], 0, s[20:21]
	v_lshl_add_u64 v[74:75], s[84:85], 0, v[68:69]
	s_mov_b64 s[20:21], 0x90010
	s_waitcnt lgkmcnt(0)
	v_mov_b32_e32 v64, v220
	v_mov_b32_e32 v65, v221
	v_mov_b32_e32 v66, v222
	v_mov_b32_e32 v67, v223
	v_lshlrev_b32_e32 v0, 16, v64
	v_and_b32_e32 v60, 0xffff0000, v64
	v_lshlrev_b32_e32 v63, 16, v66
	v_and_b32_e32 v64, 0xffff0000, v66
	v_and_b32_e32 v66, 0xffff0000, v67
	v_lshlrev_b32_e32 v61, 16, v65
	v_and_b32_e32 v62, 0xffff0000, v65
	v_lshlrev_b32_e32 v65, 16, v67
	v_mul_f32_e32 v55, v55, v66
	v_mul_f32_e32 v0, v56, v0
	v_mul_f32_e32 v56, v57, v60
	v_mul_f32_e32 v57, v58, v61
	v_mul_f32_e32 v58, v59, v62
	v_mul_f32_e32 v59, v52, v63
	v_mul_f32_e32 v60, v53, v64
	v_mul_f32_e32 v61, v54, v65
	v_cvt_pk_bf16_f32 v52, v0, v56
	v_cvt_pk_bf16_f32 v53, v57, v58
	v_cvt_pk_bf16_f32 v54, v59, v60
	v_cvt_pk_bf16_f32 v55, v61, v55
	global_store_dwordx4 v[72:73], v[52:55], off
	v_lshl_add_u64 v[56:57], v[2:3], 0, s[20:21]
	v_lshl_add_u64 v[58:59], s[84:85], 0, v[56:57]
	s_mov_b64 s[20:21], 0xa0000
	v_lshl_add_u64 v[56:57], s[22:23], 0, v[56:57]
	s_waitcnt lgkmcnt(0)
; __device__ __forceinline__ float bf_lo(unsigned w) { return __uint_as_float(w << 16); }
; __device__ __forceinline__ float bf_hi(unsigned w) { return __uint_as_float(w & 0xffff0000u); }
; #define PG8_BAR __builtin_amdgcn_s_barrier()
; __device__ __forceinline__ u32x4 pack8(const f32x4 a, const f32x4 b) { u32x4 w; w.x = cvt_pk_bf16(a[0], a[1]); w.y = cvt_pk_bf16(a[2], a[3]); w.z = cvt_pk_bf16(b[0], b[1]); w.w = cvt_pk_bf16(b[2], b[3]); return w; }
;     __device__ __forceinline__ void prepare(const pg8::Unit& u, LAS unsigned char* lds, int par, int tid) const { F.prepare(u, lds, par, tid); }
;     __device__ __forceinline__ void prepare(const pg8::Unit& u, LAS unsigned char* lds, int par, int tid) const { F.prepare(u, lds, par, tid); }
;     __device__ __forceinline__ void prepare(const pg8::Unit& u, LAS unsigned char* lds, int par, int tid) const { F.prepare(u, lds, par, tid); }
; template <class Epi>
; __device__ __forceinline__ void gemm_phase(LAS unsigned char* lds, const Gemm g, const StaticOrder& S, const Epi& E, const int tid) {
;     ...
;         if (!has_next) break;
; #pragma unroll
;         for (int a = 0; a < 2; ++a)
; #pragma unroll
;             for (int b = 0; b < 2; ++b)
; #pragma unroll
;                 for (int m = 0; m < 4; ++m)
; #pragma unroll
;                     for (int n = 0; n < 2; ++n) acc[a][b][m][n] = (f32x4){0.f, 0.f, 0.f, 0.f};
;         cur = nxt; cA = nA; cB = nB; ++ui;
;         if (Epi::TWO) { cA2 = (const char*)g.A2 + (size_t)cur.pm * tstep; cB2 = (const char*)g.Bt2 + (size_t)cur.pn * tstep; }
;         E.prepare(cur, lds, ui & 1, tid);
;         if (ALIGN_EPI) { if (wr == 1) PG8_BAR; }
;     __device__ __forceinline__ void operator()(const f32x4 (&acc)[2][2][4][2], const pg8::Unit& u, int wr, int wc, int fr, int fq, LAS unsigned char*, int) const {
;     ...
;                 for (int bj = 0; bj < 2; ++bj) {
;                     const size_t off = (size_t)(row0 + ai * 128 + m * 16) * D + c0 + bj * 8;
;                     const u32x4 b = *(const u32x4*)(sb + off);
;                     f32x4 v0 = acc[ai][bj][m][0], v1 = acc[ai][bj][m][1];
;                     v0[0] *= bf_lo(b.x); v0[1] *= bf_hi(b.x); v0[2] *= bf_lo(b.y); v0[3] *= bf_hi(b.y);
;                     v1[0] *= bf_lo(b.z); v1[1] *= bf_hi(b.z); v1[2] *= bf_lo(b.w); v1[3] *= bf_hi(b.w);
;                     *(u32x4*)(o + off) = pack8(v0, v1);
;                 }
	v_mov_b32_e32 v52, v224
	v_mov_b32_e32 v53, v225
	v_mov_b32_e32 v54, v226
	v_mov_b32_e32 v55, v227
	v_lshlrev_b32_e32 v0, 16, v52
	v_and_b32_e32 v52, 0xffff0000, v52
	v_lshlrev_b32_e32 v60, 16, v53
	v_and_b32_e32 v53, 0xffff0000, v53
	v_lshlrev_b32_e32 v61, 16, v54
	v_lshlrev_b32_e32 v62, 16, v55
	v_and_b32_e32 v55, 0xffff0000, v55
	v_and_b32_e32 v54, 0xffff0000, v54
	v_mul_f32_e32 v0, v48, v0
	v_mul_f32_e32 v48, v49, v52
	v_mul_f32_e32 v49, v50, v60
	v_mul_f32_e32 v50, v51, v53
	v_mul_f32_e32 v51, v44, v61
	v_mul_f32_e32 v47, v47, v55
	v_mul_f32_e32 v52, v45, v54
	v_mul_f32_e32 v53, v46, v62
	v_cvt_pk_bf16_f32 v44, v0, v48
	v_cvt_pk_bf16_f32 v45, v49, v50
	v_cvt_pk_bf16_f32 v46, v51, v52
	v_cvt_pk_bf16_f32 v47, v53, v47
	v_lshl_add_u64 v[54:55], s[22:23], 0, v[68:69]
	global_store_dwordx4 v[54:55], v[44:47], off
	v_lshl_add_u64 v[52:53], v[2:3], 0, s[20:21]
	v_lshl_add_u64 v[58:59], s[84:85], 0, v[52:53]
	s_mov_b64 s[20:21], 0xa0010
	s_waitcnt lgkmcnt(0)
	v_mov_b32_e32 v48, v228
	v_mov_b32_e32 v49, v229
	v_mov_b32_e32 v50, v230
	v_mov_b32_e32 v51, v231
	v_lshlrev_b32_e32 v0, 16, v48
	v_and_b32_e32 v44, 0xffff0000, v48
	v_lshlrev_b32_e32 v47, 16, v50
	v_and_b32_e32 v48, 0xffff0000, v50
	v_and_b32_e32 v50, 0xffff0000, v51
	v_lshlrev_b32_e32 v45, 16, v49
	v_and_b32_e32 v46, 0xffff0000, v49
	v_lshlrev_b32_e32 v49, 16, v51
	v_mul_f32_e32 v39, v39, v50
	v_mul_f32_e32 v0, v40, v0
	v_mul_f32_e32 v40, v41, v44
	v_mul_f32_e32 v41, v42, v45
	v_mul_f32_e32 v42, v43, v46
	v_mul_f32_e32 v43, v36, v47
	v_mul_f32_e32 v44, v37, v48
	v_mul_f32_e32 v45, v38, v49
	v_cvt_pk_bf16_f32 v36, v0, v40
	v_cvt_pk_bf16_f32 v37, v41, v42
	v_cvt_pk_bf16_f32 v38, v43, v44
	v_cvt_pk_bf16_f32 v39, v45, v39
	global_store_dwordx4 v[56:57], v[36:39], off
	v_lshl_add_u64 v[40:41], v[2:3], 0, s[20:21]
	v_lshl_add_u64 v[42:43], s[84:85], 0, v[40:41]
	s_mov_b64 s[20:21], 0xb0000
	v_lshl_add_u64 v[40:41], s[22:23], 0, v[40:41]
	s_waitcnt lgkmcnt(0)
	v_mov_b32_e32 v36, v232
	v_mov_b32_e32 v37, v233
	v_mov_b32_e32 v38, v234
	v_mov_b32_e32 v39, v235
	v_lshlrev_b32_e32 v0, 16, v36
	v_and_b32_e32 v36, 0xffff0000, v36
	v_lshlrev_b32_e32 v44, 16, v37
	v_and_b32_e32 v37, 0xffff0000, v37
	v_lshlrev_b32_e32 v45, 16, v38
	v_lshlrev_b32_e32 v46, 16, v39
	v_and_b32_e32 v39, 0xffff0000, v39
	v_and_b32_e32 v38, 0xffff0000, v38
	v_mul_f32_e32 v0, v32, v0
	v_mul_f32_e32 v32, v33, v36
	v_mul_f32_e32 v33, v34, v44
	v_mul_f32_e32 v34, v35, v37
	v_mul_f32_e32 v35, v28, v45
	v_mul_f32_e32 v31, v31, v39
	v_mul_f32_e32 v36, v29, v38
	v_mul_f32_e32 v37, v30, v46
	v_cvt_pk_bf16_f32 v28, v0, v32
	v_cvt_pk_bf16_f32 v29, v33, v34
	v_cvt_pk_bf16_f32 v30, v35, v36
	v_cvt_pk_bf16_f32 v31, v37, v31
	v_lshl_add_u64 v[38:39], s[22:23], 0, v[52:53]
	global_store_dwordx4 v[38:39], v[28:31], off
	v_lshl_add_u64 v[36:37], v[2:3], 0, s[20:21]
	v_lshl_add_u64 v[42:43], s[84:85], 0, v[36:37]
	s_mov_b64 s[20:21], 0xb0010
	v_lshl_add_u64 v[2:3], v[2:3], 0, s[20:21]
	s_waitcnt lgkmcnt(0)
	v_mov_b32_e32 v32, v236
	v_mov_b32_e32 v33, v237
	v_mov_b32_e32 v34, v238
	v_mov_b32_e32 v35, v239
	v_lshlrev_b32_e32 v0, 16, v32
	v_and_b32_e32 v28, 0xffff0000, v32
	v_lshlrev_b32_e32 v31, 16, v34
	v_and_b32_e32 v32, 0xffff0000, v34
	v_and_b32_e32 v34, 0xffff0000, v35
	v_lshlrev_b32_e32 v29, 16, v33
	v_and_b32_e32 v30, 0xffff0000, v33
	v_lshlrev_b32_e32 v33, 16, v35
	v_mul_f32_e32 v23, v23, v34
	v_mul_f32_e32 v0, v24, v0
	v_mul_f32_e32 v24, v25, v28
	v_mul_f32_e32 v25, v26, v29
	v_mul_f32_e32 v26, v27, v30
	v_mul_f32_e32 v27, v20, v31
	v_mul_f32_e32 v28, v21, v32
	v_mul_f32_e32 v29, v22, v33
	v_cvt_pk_bf16_f32 v20, v0, v24
	v_cvt_pk_bf16_f32 v21, v25, v26
	v_cvt_pk_bf16_f32 v22, v27, v28
	v_cvt_pk_bf16_f32 v23, v29, v23
	global_store_dwordx4 v[40:41], v[20:23], off
	v_lshl_add_u64 v[24:25], s[84:85], 0, v[2:3]
	s_waitcnt lgkmcnt(0)
	v_mov_b32_e32 v20, v240
	v_mov_b32_e32 v21, v241
	v_mov_b32_e32 v22, v242
	v_mov_b32_e32 v23, v243
	v_lshlrev_b32_e32 v0, 16, v20
	v_and_b32_e32 v20, 0xffff0000, v20
	v_lshlrev_b32_e32 v26, 16, v21
	v_and_b32_e32 v21, 0xffff0000, v21
	v_lshlrev_b32_e32 v27, 16, v22
	v_lshlrev_b32_e32 v28, 16, v23
	v_and_b32_e32 v23, 0xffff0000, v23
	v_and_b32_e32 v22, 0xffff0000, v22
	v_mul_f32_e32 v0, v16, v0
	v_mul_f32_e32 v16, v17, v20
	v_mul_f32_e32 v17, v18, v26
	v_mul_f32_e32 v18, v19, v21
	v_mul_f32_e32 v19, v12, v27
	v_mul_f32_e32 v15, v15, v23
	v_mul_f32_e32 v20, v13, v22
	v_mul_f32_e32 v21, v14, v28
	v_cvt_pk_bf16_f32 v12, v0, v16
	v_cvt_pk_bf16_f32 v13, v17, v18
	v_cvt_pk_bf16_f32 v14, v19, v20
	v_cvt_pk_bf16_f32 v15, v21, v15
	v_lshl_add_u64 v[20:21], s[22:23], 0, v[36:37]
	v_lshl_add_u64 v[22:23], s[22:23], 0, v[2:3]
	global_store_dwordx4 v[20:21], v[12:15], off
	s_waitcnt lgkmcnt(0)
	v_mov_b32_e32 v16, v244
	v_mov_b32_e32 v17, v245
	v_mov_b32_e32 v18, v246
	v_mov_b32_e32 v19, v247
	v_and_b32_e32 v2, 0xffff0000, v16
	v_lshlrev_b32_e32 v3, 16, v17
	v_lshlrev_b32_e32 v13, 16, v18
	v_and_b32_e32 v14, 0xffff0000, v18
	v_lshlrev_b32_e32 v0, 16, v16
	v_and_b32_e32 v12, 0xffff0000, v17
	v_lshlrev_b32_e32 v15, 16, v19
	v_and_b32_e32 v16, 0xffff0000, v19
	v_mul_f32_e32 v2, v9, v2
	v_mul_f32_e32 v3, v10, v3
	v_mul_f32_e32 v4, v4, v13
	v_mul_f32_e32 v5, v5, v14
	v_mul_f32_e32 v0, v8, v0
	v_mul_f32_e32 v8, v11, v12
	v_mul_f32_e32 v6, v6, v15
	v_mul_f32_e32 v7, v7, v16
	v_cvt_pk_bf16_f32 v2, v0, v2
	v_cvt_pk_bf16_f32 v3, v3, v8
	v_cvt_pk_bf16_f32 v4, v4, v5
	v_cvt_pk_bf16_f32 v5, v6, v7
	global_store_dwordx4 v[22:23], v[2:5], off
	s_cbranch_vccnz .LBB0_445
	s_andn2_b64 vcc, exec, s[6:7]
	s_cbranch_vccnz .LBB0_444
	s_barrier
	s_branch .LBB0_444
